# step 0: cache slice spread over all 256 workgroups instead of 172..255 (whose 192..255 also carry the memory K/V tile)
# speedup vs baseline: 1.0053x; 1.0053x over previous
; __device__ __forceinline__ void cache_convert(const Params& P, int l, int pct0, int pct1, int part, int nparts) {
;     int tid = threadIdx.x; asm volatile("" : "+v"(tid));
;     constexpr unsigned NGL = 32u * 512u * 512u / 8u;
;     const unsigned g0 = (unsigned)((unsigned long long)(2u * NGL) * pct0 / 100u), g1 = (unsigned)((unsigned long long)(2u * NGL) * pct1 / 100u);
;     const float* ck = P.in[3] + (size_t)l * 32 * 512 * 512; const float* cv = P.in[4] + (size_t)l * 32 * 512 * 512;
;     bf16_t* kb = (bf16_t*)(P.ws + WS_KB16) + (size_t)l * 32 * 512 * 512; bf16_t* vb = (bf16_t*)(P.ws + WS_VB16) + (size_t)l * 32 * 512 * 512;
;     float* ok = P.out + OFF_KS + (size_t)l * 32 * 512 * 512; float* ov = P.out + OFF_VS + (size_t)l * 32 * 512 * 512;
; #pragma unroll 8
;     for (unsigned gi = g0 + (unsigned)part * 512u + tid; gi < g1; gi += (unsigned)nparts * 512u) {
; __global__ void __launch_bounds__(512, 2) mega_fwd(Params P) {
;     ...
;         if (s == 0 || s == 2 || (s == 8 && l < NL - 1)) {
;             const int cl = s == 8 ? l + 1 : l, p0 = s == 8 ? 0 : (s == 0 ? (step == 0 ? 0 : 30) : 60), p1 = s == 8 ? 30 : (s == 0 ? 60 : 100);
;             int c0 = s == 2 ? 148 : 172; if (G <= c0) c0 = 0;
;             if (bxs >= c0) cache_convert(P, cl, p0, p1, bxs - c0, G - c0);
;         }
.LBB0_674:
	s_andn2_b64 vcc, exec, s[18:19]
	s_cbranch_vccnz .LBB0_682
	v_readlane_b32 s0, v255, 7
	v_readlane_b32 s1, v255, 8
	s_and_b64 s[0:1], s[0:1], exec
	s_movk_i32 s0, 0x94
	s_cselect_b32 s0, s0, 0xac
	s_cmp_gt_i32 s96, s0
	s_cselect_b32 s0, s0, 0
	v_readlane_b32 s1, v254, 56
	s_cmp_eq_u32 s1, 0
	s_cselect_b32 s0, 0, s0
	s_cmp_lt_i32 s68, s0
	s_cbranch_scc1 .LBB0_682
	v_readlane_b32 s2, v255, 9
	s_sub_i32 s1, s68, s0
	v_readlane_b32 s3, v255, 10
	s_and_b64 s[2:3], exec, s[2:3]
	s_cselect_b32 s2, 0, 0x99999
	s_cmp_eq_u32 s89, 0
	s_cselect_b32 s4, s2, 0x133333
	s_mov_b32 s2, 0x133333
	s_cselect_b32 s5, s2, 0x200000
	s_and_b64 s[2:3], s[6:7], exec
	s_cselect_b32 s2, 0, s4
	s_cselect_b32 s12, 0x99999, s5
	s_lshl_b32 s1, s1, 9
	v_mov_b32_e32 v0, v208
	s_add_i32 s1, s1, s2
	s_nop 0
	v_add_u32_e32 v10, s1, v0
	v_cmp_gt_u32_e32 vcc, s12, v10
	s_and_saveexec_b64 s[2:3], vcc
	s_cbranch_execz .LBB0_681
	v_cndmask_b32_e64 v0, 0, 1, s[6:7]
	v_lshlrev_b32_e32 v11, 3, v10
	v_readfirstlane_b32 s1, v0
	s_add_i32 s1, s1, s88
	s_lshl_b32 s10, s1, 23
	s_lshl_b32 s4, s1, 24
	s_add_u32 s4, s94, s4
	s_addc_u32 s5, s95, 0
	s_lshl_b32 s1, s1, 25
	s_add_u32 s6, s92, s1
	s_addc_u32 s7, s93, 0
	s_sub_i32 s1, s96, s0
	s_lshl_b32 s13, s1, 9
	s_lshl_b32 s0, s0, 12
	v_readlane_b32 s1, v254, 46
	s_sub_i32 s14, s1, s0
	s_mov_b64 s[8:9], 0
	s_lshl_b32 s62, s10, 2
	s_branch .LBB0_679
